# MLA + diff attention tile loops hand-written: software-pipelined, scalar (non-packed) softmax VALU finely interleaved behind MFMAs, 4 LDS slots
# speedup vs baseline: 1.0544x; 1.0158x over previous
; #define LAS __attribute__((address_space(3)))
; template <int DQK, int DV, int FLAGS, int qp, int kp, int vts, int op> ...
;     ...
;             __builtin_amdgcn_sched_barrier(0);
; #pragma unroll
;             for (int c = 0; c < ND0 / 2; ++c) {
;                 if (c + 1 < ND0 / 2) {
; #pragma unroll
;                     for (int i = 0; i < 2; ++i) { kf[(c + 1) & 1][2 * i] = *(const LAS bf16x8*)(kb + (2 * c + 2 + i) * 32); kf[(c + 1) & 1][2 * i + 1] = *(const LAS bf16x8*)(kb + 32 * KROW + (2 * c + 2 + i) * 32); }
;                 }
; #pragma unroll
;                 for (int i = 0; i < 2; ++i) {
;                     p0 = __builtin_amdgcn_mfma_f32_32x32x16_bf16(kf[c & 1][2 * i], qr[2 * c + i], p0, 0, 0, 0);
;                     p1 = __builtin_amdgcn_mfma_f32_32x32x16_bf16(kf[c & 1][2 * i + 1], qr[2 * c + i], p1, 0, 0, 0);
;                 }
;                 __builtin_amdgcn_sched_barrier(0);
;             }
;     ...
;             f32x2 rs2 = {0.f, 0.f};
; #pragma unroll
;             for (int r = 0; r < 16; ++r) { p0[r] = __builtin_amdgcn_exp2f(p0[r]); p1[r] = __builtin_amdgcn_exp2f(p1[r]); }
; #pragma unroll
;             for (int r = 0; r < 16; r += 2) { rs2 += (f32x2){p0[r], p0[r + 1]}; rs2 += (f32x2){p1[r], p1[r + 1]}; }
;             l += rs2.x + rs2.y;
;             bf16x8 pf[4];
;             pf[0] = pack_bf16x8(p0, 0); pf[1] = pack_bf16x8(p0, 8); pf[2] = pack_bf16x8(p1, 0); pf[3] = pack_bf16x8(p1, 8);
;             __builtin_amdgcn_sched_barrier(0);
; #pragma unroll
;             for (int d = 0; d < NDB; ++d) {
;                 if (d + 1 < NDB) {
; #pragma unroll
;                     for (int ks = 0; ks < 4; ++ks) vf[(d + 1) & 1][ks] = *(const LAS bf16x8*)(vb + (d + 1) * 32 * VROW + ks * 32);
;                 }
; #pragma unroll
;                 for (int ks = 0; ks < 4; ++ks) o[d] = __builtin_amdgcn_mfma_f32_32x32x16_bf16(vf[d & 1][ks], pf[ks], o[d], 0, 0, 0);
;                 __builtin_amdgcn_sched_barrier(0);
;             }
;         }
;         if (skip && more) ATT_GLOAD((FLAGS & AF_REV) ? t - 1 : t + 1);
;         if (more) ATT_LSTORE(cur ^ 1);
.Lq_top0:
	s_cmp_eq_u32 s3, 0
	s_cbranch_scc1 .Lq_gen0
	s_add_i32 s13, s3, 1
	s_cmp_ge_i32 s13, s20
	s_cbranch_scc1 .Lq_gen0
	s_add_i32 s12, s3, 1
	s_and_b32 s12, s12, 3
	s_mulk_i32 s12, 0x5800
	v_add3_u32 v206, s12, v169, v0
	ds_read_b128 v[96:99], v206
	ds_read_b128 v[104:107], v206 offset:6656
	ds_read_b128 v[100:103], v206 offset:32
	ds_read_b128 v[108:111], v206 offset:6688
	ds_read_b128 v[112:115], v206 offset:64
	ds_read_b128 v[120:123], v206 offset:6720
	ds_read_b128 v[116:119], v206 offset:96
	ds_read_b128 v[124:127], v206 offset:6752
	s_and_b32 s16, s3, 3
	s_mulk_i32 s16, 0x5800
	v_add3_u32 v207, s16, v171, v0
	v_mfma_f32_32x32x16_bf16 v[32:47], v[152:155], v[214:217], v[32:47]
	v_exp_f32_e32 v64, v64
	v_exp_f32_e32 v65, v65
	v_mfma_f32_32x32x16_bf16 v[16:31], v[188:191], v[214:217], v[16:31]
	v_exp_f32_e32 v80, v80
	v_exp_f32_e32 v81, v81
	v_mov_b32_e32 v204, v64
	v_mov_b32_e32 v205, v65
	v_mfma_f32_32x32x16_bf16 v[32:47], v[156:159], v[218:221], v[32:47]
	v_exp_f32_e32 v66, v66
	v_exp_f32_e32 v67, v67
	v_add_f32_e32 v204, v80, v204
	v_add_f32_e32 v205, v81, v205
	v_mfma_f32_32x32x16_bf16 v[16:31], v[192:195], v[218:221], v[16:31]
	v_exp_f32_e32 v82, v82
	v_exp_f32_e32 v83, v83
	v_add_f32_e32 v204, v66, v204
	v_add_f32_e32 v205, v67, v205
	v_mfma_f32_32x32x16_bf16 v[32:47], v[160:163], v[222:225], v[32:47]
	v_exp_f32_e32 v68, v68
	v_exp_f32_e32 v69, v69
	v_add_f32_e32 v204, v82, v204
	v_add_f32_e32 v205, v83, v205
	v_mfma_f32_32x32x16_bf16 v[16:31], v[196:199], v[222:225], v[16:31]
	v_exp_f32_e32 v84, v84
	v_exp_f32_e32 v85, v85
	v_add_f32_e32 v204, v68, v204
	v_add_f32_e32 v205, v69, v205
	v_mfma_f32_32x32x16_bf16 v[32:47], v[164:167], v[226:229], v[32:47]
	v_exp_f32_e32 v70, v70
	v_exp_f32_e32 v71, v71
	v_add_f32_e32 v204, v84, v204
	v_add_f32_e32 v205, v85, v205
	v_mfma_f32_32x32x16_bf16 v[16:31], v[200:203], v[226:229], v[16:31]
	v_exp_f32_e32 v86, v86
	v_exp_f32_e32 v87, v87
	v_add_f32_e32 v204, v70, v204
	v_add_f32_e32 v205, v71, v205
	s_add_i32 s12, s3, 2
	s_cmp_ge_i32 s12, s2
	s_cbranch_scc1 .Lq_nols_s0
	s_and_b32 s16, s12, 3
	s_mulk_i32 s16, 0x5800
	s_waitcnt vmcnt(0)
	v_add_u32_e32 v209, s16, v14
	v_add_u32_e32 v210, s16, v174
	v_add_u32_e32 v211, s16, v172
	ds_write_b128 v209, v[140:143]
	ds_write_b128 v210, v[148:151] offset:13312
	s_and_saveexec_b64 s[14:15], s[10:11]
	ds_write_b128 v211, v[144:147]
	s_or_b64 exec, exec, s[14:15]
	s_add_i32 s12, s3, 3
	s_cmp_ge_i32 s12, s2
	s_cbranch_scc1 .Lq_nols_s0
	s_and_saveexec_b64 s[14:15], s[10:11]
	global_load_dwordx4 v[144:147], v[180:181], off
	s_or_b64 exec, exec, s[14:15]
	global_load_dwordx4 v[140:143], v[178:179], off
	global_load_dwordx4 v[148:151], v[176:177], off
	s_mov_b64 s[14:15], 0x80
	v_lshl_add_u64 v[176:177], v[176:177], 0, s[14:15]
	v_lshl_add_u64 v[178:179], v[178:179], 0, s[96:97]
	v_lshl_add_u64 v[180:181], v[180:181], 0, s[96:97]
.Lq_nols_s0:
	ds_read_b128 v[152:155], v207 offset:13312
	ds_read_b128 v[156:159], v207 offset:13344
	ds_read_b128 v[160:163], v207 offset:13376
	ds_read_b128 v[164:167], v207 offset:13408
	s_waitcnt lgkmcnt(8)
	v_mfma_f32_32x32x16_bf16 v[214:229], v[96:99], v[2:5], v[48:63]
	v_exp_f32_e32 v72, v72
	v_exp_f32_e32 v73, v73
	v_add_f32_e32 v204, v86, v204
	v_add_f32_e32 v205, v87, v205
	v_mfma_f32_32x32x16_bf16 v[230:245], v[104:107], v[2:5], v[48:63]
	v_exp_f32_e32 v88, v88
	v_exp_f32_e32 v89, v89
	v_add_f32_e32 v204, v72, v204
	v_add_f32_e32 v205, v73, v205
	v_mfma_f32_32x32x16_bf16 v[214:229], v[100:103], v[6:9], v[214:229]
	v_exp_f32_e32 v74, v74
	v_exp_f32_e32 v75, v75
	v_add_f32_e32 v204, v88, v204
	v_add_f32_e32 v205, v89, v205
	v_mfma_f32_32x32x16_bf16 v[230:245], v[108:111], v[6:9], v[230:245]
	v_exp_f32_e32 v90, v90
	v_exp_f32_e32 v91, v91
	v_add_f32_e32 v204, v74, v204
	v_add_f32_e32 v205, v75, v205
	ds_read_b128 v[96:99], v206 offset:128
	ds_read_b128 v[104:107], v206 offset:6784
	ds_read_b128 v[100:103], v206 offset:160
	ds_read_b128 v[108:111], v206 offset:6816
	s_waitcnt lgkmcnt(8)
	v_mfma_f32_32x32x16_bf16 v[214:229], v[112:115], v[10:13], v[214:229]
	v_exp_f32_e32 v76, v76
	v_exp_f32_e32 v77, v77
	v_add_f32_e32 v204, v90, v204
	v_add_f32_e32 v205, v91, v205
	v_mfma_f32_32x32x16_bf16 v[230:245], v[120:123], v[10:13], v[230:245]
	v_exp_f32_e32 v92, v92
	v_exp_f32_e32 v93, v93
	v_add_f32_e32 v204, v76, v204
	v_add_f32_e32 v205, v77, v205
	v_mfma_f32_32x32x16_bf16 v[214:229], v[116:119], v[128:131], v[214:229]
	v_exp_f32_e32 v78, v78
	v_exp_f32_e32 v79, v79
	v_add_f32_e32 v204, v92, v204
	v_add_f32_e32 v205, v93, v205
	v_mfma_f32_32x32x16_bf16 v[230:245], v[124:127], v[128:131], v[230:245]
	v_exp_f32_e32 v94, v94
	v_exp_f32_e32 v95, v95
	v_add_f32_e32 v204, v78, v204
	v_add_f32_e32 v205, v79, v205
	ds_read_b128 v[188:191], v207 offset:17920
	ds_read_b128 v[192:195], v207 offset:17952
	ds_read_b128 v[196:199], v207 offset:17984
	ds_read_b128 v[200:203], v207 offset:18016
	s_waitcnt lgkmcnt(4)
	v_mfma_f32_32x32x16_bf16 v[214:229], v[96:99], v[132:135], v[214:229]
	s_nop 0
	v_add_f32_e32 v204, v94, v204
	v_add_f32_e32 v205, v95, v205
	v_cvt_pk_bf16_f32 v64, v64, v65
	v_cvt_pk_bf16_f32 v65, v66, v67
	v_cvt_pk_bf16_f32 v66, v68, v69
	v_mfma_f32_32x32x16_bf16 v[230:245], v[104:107], v[132:135], v[230:245]
	v_cvt_pk_bf16_f32 v67, v70, v71
	v_cvt_pk_bf16_f32 v68, v72, v73
	v_cvt_pk_bf16_f32 v69, v74, v75
	v_cvt_pk_bf16_f32 v70, v76, v77
	v_cvt_pk_bf16_f32 v71, v78, v79
	v_mfma_f32_32x32x16_bf16 v[214:229], v[100:103], v[136:139], v[214:229]
	v_cvt_pk_bf16_f32 v72, v80, v81
	v_cvt_pk_bf16_f32 v73, v82, v83
	v_cvt_pk_bf16_f32 v74, v84, v85
	v_cvt_pk_bf16_f32 v75, v86, v87
	v_cvt_pk_bf16_f32 v76, v88, v89
	v_mfma_f32_32x32x16_bf16 v[230:245], v[108:111], v[136:139], v[230:245]
	v_cvt_pk_bf16_f32 v77, v90, v91
	v_cvt_pk_bf16_f32 v78, v92, v93
	v_cvt_pk_bf16_f32 v79, v94, v95
	v_add_f32_e32 v208, v204, v205
	v_add_f32_e32 v175, v175, v208
	s_branch .Lq_tailb0

; template <int DQK, int DV, int FLAGS, int qp, int kp, int vts, int op> ...
;     ...
;             f32x2 rs2 = {0.f, 0.f};
; #pragma unroll
;             for (int r = 0; r < 16; ++r) { p0[r] = __builtin_amdgcn_exp2f(p0[r]); p1[r] = __builtin_amdgcn_exp2f(p1[r]); }
; #pragma unroll
;             for (int r = 0; r < 16; r += 2) { rs2 += (f32x2){p0[r], p0[r + 1]}; rs2 += (f32x2){p1[r], p1[r + 1]}; }
;             l += rs2.x + rs2.y;
;             bf16x8 pf[4];
;             pf[0] = pack_bf16x8(p0, 0); pf[1] = pack_bf16x8(p0, 8); pf[2] = pack_bf16x8(p1, 0); pf[3] = pack_bf16x8(p1, 8);
.Lq_notfirst_p0:
	v_exp_f32_e32 v64, v64
	v_exp_f32_e32 v65, v65
	v_exp_f32_e32 v80, v80
	v_exp_f32_e32 v81, v81
	v_mov_b32_e32 v204, v64
	v_mov_b32_e32 v205, v65
	v_exp_f32_e32 v66, v66
	v_exp_f32_e32 v67, v67
	v_add_f32_e32 v204, v80, v204
	v_add_f32_e32 v205, v81, v205
	v_exp_f32_e32 v82, v82
	v_exp_f32_e32 v83, v83
	v_add_f32_e32 v204, v66, v204
	v_add_f32_e32 v205, v67, v205
	v_exp_f32_e32 v68, v68
	v_exp_f32_e32 v69, v69
	v_add_f32_e32 v204, v82, v204
	v_add_f32_e32 v205, v83, v205
	v_exp_f32_e32 v84, v84
	v_exp_f32_e32 v85, v85
	v_add_f32_e32 v204, v68, v204
	v_add_f32_e32 v205, v69, v205
	v_exp_f32_e32 v70, v70
	v_exp_f32_e32 v71, v71
	v_add_f32_e32 v204, v84, v204
	v_add_f32_e32 v205, v85, v205
	v_exp_f32_e32 v86, v86
	v_exp_f32_e32 v87, v87
	v_add_f32_e32 v204, v70, v204
	v_add_f32_e32 v205, v71, v205
	v_exp_f32_e32 v72, v72
	v_exp_f32_e32 v73, v73
	v_add_f32_e32 v204, v86, v204
	v_add_f32_e32 v205, v87, v205
	v_exp_f32_e32 v88, v88
	v_exp_f32_e32 v89, v89
	v_add_f32_e32 v204, v72, v204
	v_add_f32_e32 v205, v73, v205
	v_exp_f32_e32 v74, v74
	v_exp_f32_e32 v75, v75
	v_add_f32_e32 v204, v88, v204
	v_add_f32_e32 v205, v89, v205
	v_exp_f32_e32 v90, v90
	v_exp_f32_e32 v91, v91
	v_add_f32_e32 v204, v74, v204
	v_add_f32_e32 v205, v75, v205
	v_exp_f32_e32 v76, v76
	v_exp_f32_e32 v77, v77
	v_add_f32_e32 v204, v90, v204
	v_add_f32_e32 v205, v91, v205
	v_exp_f32_e32 v92, v92
	v_exp_f32_e32 v93, v93
	v_add_f32_e32 v204, v76, v204
	v_add_f32_e32 v205, v77, v205
	v_exp_f32_e32 v78, v78
	v_exp_f32_e32 v79, v79
	v_add_f32_e32 v204, v92, v204
	v_add_f32_e32 v205, v93, v205
	v_exp_f32_e32 v94, v94
	v_exp_f32_e32 v95, v95
	v_add_f32_e32 v204, v78, v204
	v_add_f32_e32 v205, v79, v205
	s_nop 0
	v_add_f32_e32 v204, v94, v204
	v_add_f32_e32 v205, v95, v205
	v_cvt_pk_bf16_f32 v64, v64, v65
	v_cvt_pk_bf16_f32 v65, v66, v67
	v_cvt_pk_bf16_f32 v66, v68, v69
	v_cvt_pk_bf16_f32 v67, v70, v71
	v_cvt_pk_bf16_f32 v68, v72, v73
	v_cvt_pk_bf16_f32 v69, v74, v75
	v_cvt_pk_bf16_f32 v70, v76, v77
	v_cvt_pk_bf16_f32 v71, v78, v79
	v_cvt_pk_bf16_f32 v72, v80, v81
	v_cvt_pk_bf16_f32 v73, v82, v83
	v_cvt_pk_bf16_f32 v74, v84, v85
	v_cvt_pk_bf16_f32 v75, v86, v87
	v_cvt_pk_bf16_f32 v76, v88, v89
	v_cvt_pk_bf16_f32 v77, v90, v91
	v_cvt_pk_bf16_f32 v78, v92, v93
	v_cvt_pk_bf16_f32 v79, v94, v95
	v_add_f32_e32 v208, v204, v205
	v_add_f32_e32 v175, v175, v208

; #define LAS __attribute__((address_space(3)))
; template <int DQK, int DV, int FLAGS, int qp, int kp, int vts, int op> ...
;     ...
;             __builtin_amdgcn_sched_barrier(0);
; #pragma unroll
;             for (int c = 0; c < ND0 / 2; ++c) {
;                 if (c + 1 < ND0 / 2) {
; #pragma unroll
;                     for (int i = 0; i < 2; ++i) { kf[(c + 1) & 1][2 * i] = *(const LAS bf16x8*)(kb + (2 * c + 2 + i) * 32); kf[(c + 1) & 1][2 * i + 1] = *(const LAS bf16x8*)(kb + 32 * KROW + (2 * c + 2 + i) * 32); }
;                 }
; #pragma unroll
;                 for (int i = 0; i < 2; ++i) {
;                     p0 = __builtin_amdgcn_mfma_f32_32x32x16_bf16(kf[c & 1][2 * i], qr[2 * c + i], p0, 0, 0, 0);
;                     p1 = __builtin_amdgcn_mfma_f32_32x32x16_bf16(kf[c & 1][2 * i + 1], qr[2 * c + i], p1, 0, 0, 0);
;                 }
;                 __builtin_amdgcn_sched_barrier(0);
;             }
;     ...
;             f32x2 rs2 = {0.f, 0.f};
; #pragma unroll
;             for (int r = 0; r < 16; ++r) { p0[r] = __builtin_amdgcn_exp2f(p0[r]); p1[r] = __builtin_amdgcn_exp2f(p1[r]); }
; #pragma unroll
;             for (int r = 0; r < 16; r += 2) { rs2 += (f32x2){p0[r], p0[r + 1]}; rs2 += (f32x2){p1[r], p1[r + 1]}; }
;             l += rs2.x + rs2.y;
;             bf16x8 pf[4];
;             pf[0] = pack_bf16x8(p0, 0); pf[1] = pack_bf16x8(p0, 8); pf[2] = pack_bf16x8(p1, 0); pf[3] = pack_bf16x8(p1, 8);
;             __builtin_amdgcn_sched_barrier(0);
; #pragma unroll
;             for (int d = 0; d < NDB; ++d) {
;                 if (d + 1 < NDB) {
; #pragma unroll
;                     for (int ks = 0; ks < 4; ++ks) vf[(d + 1) & 1][ks] = *(const LAS bf16x8*)(vb + (d + 1) * 32 * VROW + ks * 32);
;                 }
; #pragma unroll
;                 for (int ks = 0; ks < 4; ++ks) o[d] = __builtin_amdgcn_mfma_f32_32x32x16_bf16(vf[d & 1][ks], pf[ks], o[d], 0, 0, 0);
;                 __builtin_amdgcn_sched_barrier(0);
;             }
.Lq_top1:
	s_cmp_eq_u32 s3, 0
	s_cbranch_scc1 .Lq_gen1
	s_add_i32 s13, s3, 1
	s_cmp_ge_i32 s13, s20
	s_cbranch_scc1 .Lq_gen1
	s_add_i32 s12, s3, 1
	s_and_b32 s12, s12, 3
	s_mulk_i32 s12, 0x5800
	v_add3_u32 v206, s12, v169, v0
	ds_read_b128 v[96:99], v206
	ds_read_b128 v[104:107], v206 offset:6656
	ds_read_b128 v[100:103], v206 offset:32
	ds_read_b128 v[108:111], v206 offset:6688
	ds_read_b128 v[112:115], v206 offset:64
	ds_read_b128 v[120:123], v206 offset:6720
	ds_read_b128 v[116:119], v206 offset:96
	ds_read_b128 v[124:127], v206 offset:6752
	s_and_b32 s16, s3, 3
	s_mulk_i32 s16, 0x5800
	v_add3_u32 v207, s16, v171, v0
	v_mfma_f32_32x32x16_bf16 v[32:47], v[152:155], v[64:67], v[32:47]
	v_exp_f32_e32 v214, v214
	v_exp_f32_e32 v215, v215
	v_mfma_f32_32x32x16_bf16 v[16:31], v[188:191], v[64:67], v[16:31]
	v_exp_f32_e32 v230, v230
	v_exp_f32_e32 v231, v231
	v_mov_b32_e32 v204, v214
	v_mov_b32_e32 v205, v215
	v_mfma_f32_32x32x16_bf16 v[32:47], v[156:159], v[68:71], v[32:47]
	v_exp_f32_e32 v216, v216
	v_exp_f32_e32 v217, v217
	v_add_f32_e32 v204, v230, v204
	v_add_f32_e32 v205, v231, v205
	v_mfma_f32_32x32x16_bf16 v[16:31], v[192:195], v[68:71], v[16:31]
	v_exp_f32_e32 v232, v232
	v_exp_f32_e32 v233, v233
	v_add_f32_e32 v204, v216, v204
	v_add_f32_e32 v205, v217, v205
	v_mfma_f32_32x32x16_bf16 v[32:47], v[160:163], v[72:75], v[32:47]
	v_exp_f32_e32 v218, v218
	v_exp_f32_e32 v219, v219
	v_add_f32_e32 v204, v232, v204
	v_add_f32_e32 v205, v233, v205
	v_mfma_f32_32x32x16_bf16 v[16:31], v[196:199], v[72:75], v[16:31]
	v_exp_f32_e32 v234, v234
	v_exp_f32_e32 v235, v235
	v_add_f32_e32 v204, v218, v204
	v_add_f32_e32 v205, v219, v205
	v_mfma_f32_32x32x16_bf16 v[32:47], v[164:167], v[76:79], v[32:47]
	v_exp_f32_e32 v220, v220
	v_exp_f32_e32 v221, v221
	v_add_f32_e32 v204, v234, v204
	v_add_f32_e32 v205, v235, v205
	v_mfma_f32_32x32x16_bf16 v[16:31], v[200:203], v[76:79], v[16:31]
	v_exp_f32_e32 v236, v236
	v_exp_f32_e32 v237, v237
	v_add_f32_e32 v204, v220, v204
	v_add_f32_e32 v205, v221, v205
	s_add_i32 s12, s3, 2
	s_cmp_ge_i32 s12, s2
	s_cbranch_scc1 .Lq_nols_s1
	s_and_b32 s16, s12, 3
	s_mulk_i32 s16, 0x5800
	s_waitcnt vmcnt(0)
	v_add_u32_e32 v209, s16, v14
	v_add_u32_e32 v210, s16, v174
	v_add_u32_e32 v211, s16, v172
	ds_write_b128 v209, v[140:143]
	ds_write_b128 v210, v[148:151] offset:13312
	s_and_saveexec_b64 s[14:15], s[10:11]
	ds_write_b128 v211, v[144:147]
	s_or_b64 exec, exec, s[14:15]
	s_add_i32 s12, s3, 3
	s_cmp_ge_i32 s12, s2
	s_cbranch_scc1 .Lq_nols_s1
	s_and_saveexec_b64 s[14:15], s[10:11]
	global_load_dwordx4 v[144:147], v[180:181], off
	s_or_b64 exec, exec, s[14:15]
	global_load_dwordx4 v[140:143], v[178:179], off
	global_load_dwordx4 v[148:151], v[176:177], off
	s_mov_b64 s[14:15], 0x80
	v_lshl_add_u64 v[176:177], v[176:177], 0, s[14:15]
	v_lshl_add_u64 v[178:179], v[178:179], 0, s[96:97]
	v_lshl_add_u64 v[180:181], v[180:181], 0, s[96:97]
.Lq_nols_s1:
	ds_read_b128 v[152:155], v207 offset:13312
	ds_read_b128 v[156:159], v207 offset:13344
	ds_read_b128 v[160:163], v207 offset:13376
	ds_read_b128 v[164:167], v207 offset:13408
	s_waitcnt lgkmcnt(8)
	v_mfma_f32_32x32x16_bf16 v[64:79], v[96:99], v[2:5], v[48:63]
	v_exp_f32_e32 v222, v222
	v_exp_f32_e32 v223, v223
	v_add_f32_e32 v204, v236, v204
	v_add_f32_e32 v205, v237, v205
	v_mfma_f32_32x32x16_bf16 v[80:95], v[104:107], v[2:5], v[48:63]
	v_exp_f32_e32 v238, v238
	v_exp_f32_e32 v239, v239
	v_add_f32_e32 v204, v222, v204
	v_add_f32_e32 v205, v223, v205
	v_mfma_f32_32x32x16_bf16 v[64:79], v[100:103], v[6:9], v[64:79]
	v_exp_f32_e32 v224, v224
	v_exp_f32_e32 v225, v225
	v_add_f32_e32 v204, v238, v204
	v_add_f32_e32 v205, v239, v205
	v_mfma_f32_32x32x16_bf16 v[80:95], v[108:111], v[6:9], v[80:95]
	v_exp_f32_e32 v240, v240
	v_exp_f32_e32 v241, v241
	v_add_f32_e32 v204, v224, v204
	v_add_f32_e32 v205, v225, v205
	ds_read_b128 v[96:99], v206 offset:128
	ds_read_b128 v[104:107], v206 offset:6784
	ds_read_b128 v[100:103], v206 offset:160
	ds_read_b128 v[108:111], v206 offset:6816
	s_waitcnt lgkmcnt(8)
	v_mfma_f32_32x32x16_bf16 v[64:79], v[112:115], v[10:13], v[64:79]
	v_exp_f32_e32 v226, v226
	v_exp_f32_e32 v227, v227
	v_add_f32_e32 v204, v240, v204
	v_add_f32_e32 v205, v241, v205
	v_mfma_f32_32x32x16_bf16 v[80:95], v[120:123], v[10:13], v[80:95]
	v_exp_f32_e32 v242, v242
	v_exp_f32_e32 v243, v243
	v_add_f32_e32 v204, v226, v204
	v_add_f32_e32 v205, v227, v205
	v_mfma_f32_32x32x16_bf16 v[64:79], v[116:119], v[128:131], v[64:79]
	v_exp_f32_e32 v228, v228
	v_exp_f32_e32 v229, v229
	v_add_f32_e32 v204, v242, v204
	v_add_f32_e32 v205, v243, v205
	v_mfma_f32_32x32x16_bf16 v[80:95], v[124:127], v[128:131], v[80:95]
	v_exp_f32_e32 v244, v244
	v_exp_f32_e32 v245, v245
	v_add_f32_e32 v204, v228, v204
	v_add_f32_e32 v205, v229, v205
	ds_read_b128 v[188:191], v207 offset:17920
	ds_read_b128 v[192:195], v207 offset:17952
	ds_read_b128 v[196:199], v207 offset:17984
	ds_read_b128 v[200:203], v207 offset:18016
	s_waitcnt lgkmcnt(4)
	v_mfma_f32_32x32x16_bf16 v[64:79], v[96:99], v[132:135], v[64:79]
	s_nop 0
	v_add_f32_e32 v204, v244, v204
	v_add_f32_e32 v205, v245, v205
	v_cvt_pk_bf16_f32 v214, v214, v215
	v_cvt_pk_bf16_f32 v215, v216, v217
	v_cvt_pk_bf16_f32 v216, v218, v219
	v_mfma_f32_32x32x16_bf16 v[80:95], v[104:107], v[132:135], v[80:95]
	v_cvt_pk_bf16_f32 v217, v220, v221
	v_cvt_pk_bf16_f32 v218, v222, v223
	v_cvt_pk_bf16_f32 v219, v224, v225
	v_cvt_pk_bf16_f32 v220, v226, v227
	v_cvt_pk_bf16_f32 v221, v228, v229
	v_mfma_f32_32x32x16_bf16 v[64:79], v[100:103], v[136:139], v[64:79]
	v_cvt_pk_bf16_f32 v222, v230, v231
	v_cvt_pk_bf16_f32 v223, v232, v233
	v_cvt_pk_bf16_f32 v224, v234, v235
	v_cvt_pk_bf16_f32 v225, v236, v237
	v_cvt_pk_bf16_f32 v226, v238, v239
	v_mfma_f32_32x32x16_bf16 v[80:95], v[108:111], v[136:139], v[80:95]
	v_cvt_pk_bf16_f32 v227, v240, v241
	v_cvt_pk_bf16_f32 v228, v242, v243
	v_cvt_pk_bf16_f32 v229, v244, v245
	v_add_f32_e32 v208, v204, v205
	v_add_f32_e32 v175, v175, v208
	s_branch .Lq_tailb1

; template <int DQK, int DV, int FLAGS, int qp, int kp, int vts, int op> ...
;     ...
;             f32x2 rs2 = {0.f, 0.f};
; #pragma unroll
;             for (int r = 0; r < 16; ++r) { p0[r] = __builtin_amdgcn_exp2f(p0[r]); p1[r] = __builtin_amdgcn_exp2f(p1[r]); }
; #pragma unroll
;             for (int r = 0; r < 16; r += 2) { rs2 += (f32x2){p0[r], p0[r + 1]}; rs2 += (f32x2){p1[r], p1[r + 1]}; }
;             l += rs2.x + rs2.y;
;             bf16x8 pf[4];
;             pf[0] = pack_bf16x8(p0, 0); pf[1] = pack_bf16x8(p0, 8); pf[2] = pack_bf16x8(p1, 0); pf[3] = pack_bf16x8(p1, 8);
.Lq_notfirst_p1:
	v_exp_f32_e32 v214, v214
	v_exp_f32_e32 v215, v215
	v_exp_f32_e32 v230, v230
	v_exp_f32_e32 v231, v231
	v_mov_b32_e32 v204, v214
	v_mov_b32_e32 v205, v215
	v_exp_f32_e32 v216, v216
	v_exp_f32_e32 v217, v217
	v_add_f32_e32 v204, v230, v204
	v_add_f32_e32 v205, v231, v205
	v_exp_f32_e32 v232, v232
	v_exp_f32_e32 v233, v233
	v_add_f32_e32 v204, v216, v204
	v_add_f32_e32 v205, v217, v205
	v_exp_f32_e32 v218, v218
	v_exp_f32_e32 v219, v219
	v_add_f32_e32 v204, v232, v204
	v_add_f32_e32 v205, v233, v205
	v_exp_f32_e32 v234, v234
	v_exp_f32_e32 v235, v235
	v_add_f32_e32 v204, v218, v204
	v_add_f32_e32 v205, v219, v205
	v_exp_f32_e32 v220, v220
	v_exp_f32_e32 v221, v221
	v_add_f32_e32 v204, v234, v204
	v_add_f32_e32 v205, v235, v205
	v_exp_f32_e32 v236, v236
	v_exp_f32_e32 v237, v237
	v_add_f32_e32 v204, v220, v204
	v_add_f32_e32 v205, v221, v205
	v_exp_f32_e32 v222, v222
	v_exp_f32_e32 v223, v223
	v_add_f32_e32 v204, v236, v204
	v_add_f32_e32 v205, v237, v205
	v_exp_f32_e32 v238, v238
	v_exp_f32_e32 v239, v239
	v_add_f32_e32 v204, v222, v204
	v_add_f32_e32 v205, v223, v205
	v_exp_f32_e32 v224, v224
	v_exp_f32_e32 v225, v225
	v_add_f32_e32 v204, v238, v204
	v_add_f32_e32 v205, v239, v205
	v_exp_f32_e32 v240, v240
	v_exp_f32_e32 v241, v241
	v_add_f32_e32 v204, v224, v204
	v_add_f32_e32 v205, v225, v205
	v_exp_f32_e32 v226, v226
	v_exp_f32_e32 v227, v227
	v_add_f32_e32 v204, v240, v204
	v_add_f32_e32 v205, v241, v205
	v_exp_f32_e32 v242, v242
	v_exp_f32_e32 v243, v243
	v_add_f32_e32 v204, v226, v204
	v_add_f32_e32 v205, v227, v205
	v_exp_f32_e32 v228, v228
	v_exp_f32_e32 v229, v229
	v_add_f32_e32 v204, v242, v204
	v_add_f32_e32 v205, v243, v205
	v_exp_f32_e32 v244, v244
	v_exp_f32_e32 v245, v245
	v_add_f32_e32 v204, v228, v204
	v_add_f32_e32 v205, v229, v205
	s_nop 0
	v_add_f32_e32 v204, v244, v204
	v_add_f32_e32 v205, v245, v205
	v_cvt_pk_bf16_f32 v214, v214, v215
	v_cvt_pk_bf16_f32 v215, v216, v217
	v_cvt_pk_bf16_f32 v216, v218, v219
	v_cvt_pk_bf16_f32 v217, v220, v221
	v_cvt_pk_bf16_f32 v218, v222, v223
	v_cvt_pk_bf16_f32 v219, v224, v225
	v_cvt_pk_bf16_f32 v220, v226, v227
	v_cvt_pk_bf16_f32 v221, v228, v229
	v_cvt_pk_bf16_f32 v222, v230, v231
	v_cvt_pk_bf16_f32 v223, v232, v233
	v_cvt_pk_bf16_f32 v224, v234, v235
	v_cvt_pk_bf16_f32 v225, v236, v237
	v_cvt_pk_bf16_f32 v226, v238, v239
	v_cvt_pk_bf16_f32 v227, v240, v241
	v_cvt_pk_bf16_f32 v228, v242, v243
	v_cvt_pk_bf16_f32 v229, v244, v245
	v_add_f32_e32 v208, v204, v205
	v_add_f32_e32 v175, v175, v208

; template <int DQK, int DV, int FLAGS, int qp, int kp, int vts, int op> ...
;     ...
;     float m = (FLAGS & AF_ROBUST) ? -1e30f : 0.f, l = 0.f;
;     f32x16 negm;
; #pragma unroll
;     for (int r = 0; r < 16; ++r) negm[r] = 0.f;
;     u32x4 kreg[KPT], vreg[VPT];
;     unsigned kgo[KPT], vgo[VPT], klo[KPT], vlo[VPT];
; #pragma unroll
;     for (int i = 0; i < KPT; ++i) { const int c = tid + i * NTHREADS; const int row = c / KC, cc = c % KC; kgo[i] = (unsigned)(row * kp + cc * 8) * 2u; klo[i] = (unsigned)(row * KROW + cc * 16); }
; #pragma unroll
;     for (int i = 0; i < VPT; ++i) { const int c = tid + i * NTHREADS; const int d = c >> 3, cc = c & 7; vgo[i] = (unsigned)(d * vts + cc * 8) * 2u; vlo[i] = (unsigned)(KT_BYTES + d * VROW + cc * 16); }
;     ...
;     ATT_GLOAD((FLAGS & AF_REV) ? kt_hi - 1 : kt_lo); ATT_LSTORE(0);
;     __syncthreads();
;     bool started = false;
;     const int prow = (r32 & ~12) | ((r32 & 4) << 1) | ((r32 & 8) >> 1);
;     const int ntile = kt_hi - kt_lo;
;     for (int it = 0; it < ntile; ++it) {
;         const int t = (FLAGS & AF_REV) ? kt_hi - 1 - it : kt_lo + it;
;         const int cur = it & 1;
;         const bool more = (it + 1 < ntile);
;         const int kv0 = t * 64;
;         bool skip = false;
;         if (FLAGS & AF_CAUSAL) skip = skip || (kv0 > qmax_w);
;         if (FLAGS & AF_WINDOW) skip = skip || (kv0 + 63 < qmin_w - (SWA_W - 1));
;         if (!skip) {
;             const LAS unsigned char* kb = lds + cur * BUF + prow * KROW + 16 * hi;
;             const LAS unsigned char* vb = lds + cur * BUF + KT_BYTES + r32 * VROW + 16 * hi;
;             f32x16 p0, p1;
;             bf16x8 kf[2][4];
; #pragma unroll
;             for (int i = 0; i < 2; ++i) { kf[0][2 * i] = *(const LAS bf16x8*)(kb + i * 32); kf[0][2 * i + 1] = *(const LAS bf16x8*)(kb + 32 * KROW + i * 32); }
;             const int nrel = qpos - kv0 - 8 * hi;
;             if (FLAGS & AF_ALIBI) { const float ab = -slope2 * (float)nrel - ((FLAGS & AF_ROBUST) ? 0.f : m);
; #pragma unroll
;                 for (int r = 0; r < 16; ++r) { const float c = (float)(16 * (r >> 3) + (r & 7)); p0[r] = __builtin_fmaf(slope2, c, ab); p1[r] = __builtin_fmaf(slope2, c + 32.f, ab); }
;             } else if (FLAGS & AF_ROBUST) {
; #pragma unroll
;                 for (int r = 0; r < 16; ++r) { p0[r] = 0.f; p1[r] = 0.f; }
;             } else { p0 = negm; p1 = negm; }
.LBB0_933:
	s_andn2_b64 vcc, exec, s[8:9]
	v_lshlrev_b32_e32 v198, 3, v17
	s_cbranch_vccnz .LBB0_923
	v_and_b32_e32 v18, 31, v15
	v_and_b32_e32 v19, 19, v15
	v_lshlrev_b32_e32 v20, 1, v15
	v_lshrrev_b32_e32 v15, 1, v15
	s_and_b32 s8, s2, 0xffffffe0
	v_readlane_b32 s12, v255, 39
	v_and_b32_e32 v20, 8, v20
	v_and_b32_e32 v15, 4, v15
	v_mov_b32_e32 v17, v1
	s_add_i32 s20, s8, s12
	v_or3_b32 v15, v19, v20, v15
	s_addk_i32 s8, 0xff40
	v_mov_b32_e32 v64, v1
	v_mov_b32_e32 v65, v1
	v_mul_u32_u24_e32 v201, 0x90, v15
	v_mul_u32_u24_e32 v203, 0x90, v18
	v_lshl_add_u64 v[206:207], s[6:7], 0, v[16:17]
	v_add_u32_e32 v15, s8, v18
	v_mov_b32_e32 v66, v1
	v_mov_b32_e32 v67, v1
	v_mov_b32_e32 v68, v1
	v_mov_b32_e32 v69, v1
	v_mov_b32_e32 v70, v1
	v_mov_b32_e32 v71, v1
	v_mov_b32_e32 v72, v1
	v_mov_b32_e32 v73, v1
	v_mov_b32_e32 v74, v1
	v_mov_b32_e32 v75, v1
	v_mov_b32_e32 v76, v1
	v_mov_b32_e32 v77, v1
	v_mov_b32_e32 v78, v1
	v_mov_b32_e32 v79, v1
	v_mov_b64_e32 v[48:49], v[64:65]
	v_mov_b64_e32 v[32:33], v[64:65]
	v_mov_b64_e32 v[16:17], v[64:65]
	v_mov_b32_e32 v197, v1
	s_or_b32 s21, s20, 31
	s_add_i32 s2, s3, 0xff
	s_addk_i32 s3, 0x100
	v_mov_b32_e32 v208, v14
	v_mov_b32_e32 v209, v14
	v_mov_b32_e32 v210, v14
	v_mov_b32_e32 v211, v14
	s_sub_i32 s34, 0xfe, s11
	v_sub_u32_e32 v205, v15, v198
	s_sub_i32 s22, 0x3fff, s10
	s_mov_b32 s23, 0
	s_mov_b64 s[36:37], 0
	v_mov_b32_e32 v222, 0
	v_mov_b64_e32 v[50:51], v[66:67]
	v_mov_b64_e32 v[52:53], v[68:69]
	v_mov_b64_e32 v[54:55], v[70:71]
	v_mov_b64_e32 v[56:57], v[72:73]
	v_mov_b64_e32 v[58:59], v[74:75]
	v_mov_b64_e32 v[60:61], v[76:77]
	v_mov_b64_e32 v[62:63], v[78:79]
	v_mov_b64_e32 v[34:35], v[66:67]
	v_mov_b64_e32 v[36:37], v[68:69]
	v_mov_b64_e32 v[38:39], v[70:71]
	v_mov_b64_e32 v[40:41], v[72:73]
	v_mov_b64_e32 v[42:43], v[74:75]
	v_mov_b64_e32 v[44:45], v[76:77]
	v_mov_b64_e32 v[46:47], v[78:79]
	v_mov_b64_e32 v[18:19], v[66:67]
	v_mov_b64_e32 v[20:21], v[68:69]
	v_mov_b64_e32 v[22:23], v[70:71]
	v_mov_b64_e32 v[24:25], v[72:73]
	v_mov_b64_e32 v[26:27], v[74:75]
	v_mov_b64_e32 v[28:29], v[76:77]
	v_mov_b64_e32 v[30:31], v[78:79]
	v_mov_b32_e32 v199, 0
	v_readlane_b32 s13, v255, 40
	s_andn2_b64 vcc, exec, s[40:41]
	s_cbranch_vccnz .Ld_fallback
	s_ashr_i32 s35, s34, 31
	s_lshl_b64 s[6:7], s[34:35], 17
	s_lshl_b64 s[10:11], s[34:35], 7
	s_add_u32 s10, s18, s10
	s_addc_u32 s11, s19, s11
	v_lshl_add_u64 v[246:247], v[206:207], 0, s[6:7]
	global_load_dwordx4 v[148:151], v[246:247], off
	v_lshl_add_u64 v[246:247], s[10:11], 0, v[0:1]
	global_load_dwordx4 v[152:155], v[246:247], off
	v_lshl_add_u64 v[246:247], s[10:11], 0, v[196:197]
	global_load_dwordx4 v[156:159], v[246:247], off
	s_add_i32 s34, s34, -1
	s_movk_i32 s13, 0x6c00
	s_waitcnt vmcnt(0)
	v_add_u32_e32 v248, s13, v204
	v_add_u32_e32 v249, s13, v200
	v_add_u32_e32 v250, s13, v202
	ds_write_b128 v248, v[148:151]
	ds_write_b128 v249, v[152:155] offset:9216
	ds_write_b128 v250, v[156:159] offset:9216
	s_ashr_i32 s35, s34, 31
	s_lshl_b64 s[6:7], s[34:35], 17
	s_lshl_b64 s[10:11], s[34:35], 7
	s_add_u32 s10, s18, s10
	s_addc_u32 s11, s19, s11
	v_lshl_add_u64 v[246:247], v[206:207], 0, s[6:7]
	global_load_dwordx4 v[148:151], v[246:247], off
	v_lshl_add_u64 v[246:247], s[10:11], 0, v[0:1]
	global_load_dwordx4 v[152:155], v[246:247], off
	v_lshl_add_u64 v[246:247], s[10:11], 0, v[196:197]
	global_load_dwordx4 v[156:159], v[246:247], off
	s_add_i32 s34, s34, -1
	s_mov_b32 s8, 0x42000000
	s_mov_b32 s9, 0x42040000
	s_sub_i32 s24, s22, s21
	s_ashr_i32 s24, s24, 6
	s_max_i32 s24, s24, 0
	s_waitcnt lgkmcnt(0)
	s_barrier
	s_cmp_lg_u32 s24, 0
	s_cbranch_scc1 .Ld_noqk0
	v_add_u32_e32 v244, v201, v194
	ds_read_b128 v[160:163], v244 offset:0
	ds_read_b128 v[164:167], v244 offset:32
	ds_read_b128 v[168:171], v244 offset:64
	ds_read_b128 v[172:175], v244 offset:96
	ds_read_b128 v[224:227], v244 offset:4608
	ds_read_b128 v[228:231], v244 offset:4640
	ds_read_b128 v[232:235], v244 offset:4672
	ds_read_b128 v[236:239], v244 offset:4704
	v_cvt_f32_i32_e32 v246, v205
	v_fma_f32 v242, -v14, v246, -v222
	v_mov_b32_e32 v80, v242
	v_add_f32_e32 v81, v14, v242
	v_fma_f32 v82, v14, s62, v242
	v_fma_f32 v83, v14, s63, v242
	v_fma_f32 v84, v14, s64, v242
	v_fma_f32 v85, v14, s65, v242
	v_fma_f32 v86, v14, s66, v242
	v_fma_f32 v87, v14, s67, v242
	v_fma_f32 v88, v14, s68, v242
	v_fma_f32 v89, v14, s69, v242
	v_fma_f32 v90, v14, s70, v242
	v_fma_f32 v91, v14, s71, v242
	v_fma_f32 v92, v14, s72, v242
	v_fma_f32 v93, v14, s73, v242
	v_fma_f32 v94, v14, s76, v242
	v_fma_f32 v95, v14, s77, v242
	v_fma_f32 v96, v14, s8, v242
	v_fma_f32 v97, v14, s9, v242
	v_fma_f32 v98, v14, s96, v242
	v_fma_f32 v99, v14, s97, v242
	v_fma_f32 v100, v14, s94, v242
	v_fma_f32 v101, v14, s95, v242
	v_fma_f32 v102, v14, s92, v242
	v_fma_f32 v103, v14, s93, v242
	v_fma_f32 v104, v14, s90, v242
	v_fma_f32 v105, v14, s91, v242
	v_fma_f32 v106, v14, s88, v242
	v_fma_f32 v107, v14, s89, v242
	v_fma_f32 v108, v14, s86, v242
	v_fma_f32 v109, v14, s87, v242
	v_fma_f32 v110, v14, s78, v242
	v_fma_f32 v111, v14, s79, v242
	s_waitcnt lgkmcnt(0)
	v_mfma_f32_32x32x16_bf16 v[80:95], v[160:163], v[2:5], v[80:95]
	v_mfma_f32_32x32x16_bf16 v[96:111], v[224:227], v[2:5], v[96:111]
	v_mfma_f32_32x32x16_bf16 v[80:95], v[164:167], v[6:9], v[80:95]
	v_mfma_f32_32x32x16_bf16 v[96:111], v[228:231], v[6:9], v[96:111]
	v_mfma_f32_32x32x16_bf16 v[80:95], v[168:171], v[10:13], v[80:95]
	v_mfma_f32_32x32x16_bf16 v[96:111], v[232:235], v[10:13], v[96:111]
	v_mfma_f32_32x32x16_bf16 v[80:95], v[172:175], v[144:147], v[80:95]
	v_mfma_f32_32x32x16_bf16 v[96:111], v[236:239], v[144:147], v[96:111]
; #define ATT_LSTORE(buf) do { LAS unsigned char* b_ = lds + (buf) * BUF; \
;         _Pragma("unroll") for (int i = 0; i < KPT; ++i) { if (KCH % NTHREADS == 0 || tid + i * NTHREADS < KCH) *(LAS u32x4*)(b_ + klo[i]) = kreg[i]; } \
;         _Pragma("unroll") for (int i = 0; i < VPT; ++i) *(LAS u32x4*)(b_ + vlo[i]) = vreg[i]; } while (0)
; template <int DQK, int DV, int FLAGS, int qp, int kp, int vts, int op> ...
;     ...
;     ATT_GLOAD((FLAGS & AF_REV) ? kt_hi - 1 : kt_lo); ATT_LSTORE(0);
;     ...
;         if (skip && more) ATT_GLOAD((FLAGS & AF_REV) ? t - 1 : t + 1);
;         if (more) ATT_LSTORE(cur ^ 1);
.Ld_noqk0:
.Ld_top0:
	s_add_i32 s12, s23, 2
	s_cmp_ge_i32 s12, s3
	s_cbranch_scc1 .Ld_nols_p0
	s_and_b32 s13, s12, 3
	s_mulk_i32 s13, 0x6c00
	s_waitcnt vmcnt(0)
	v_add_u32_e32 v248, s13, v204
	v_add_u32_e32 v249, s13, v200
	v_add_u32_e32 v250, s13, v202
	ds_write_b128 v248, v[148:151]
	ds_write_b128 v249, v[152:155] offset:9216
	ds_write_b128 v250, v[156:159] offset:9216
	s_add_i32 s12, s23, 3
	s_cmp_ge_i32 s12, s3
	s_cbranch_scc1 .Ld_nols_p0
	s_ashr_i32 s35, s34, 31
	s_lshl_b64 s[6:7], s[34:35], 17
	s_lshl_b64 s[10:11], s[34:35], 7
	s_add_u32 s10, s18, s10
	s_addc_u32 s11, s19, s11
	v_lshl_add_u64 v[246:247], v[206:207], 0, s[6:7]
	global_load_dwordx4 v[148:151], v[246:247], off
	v_lshl_add_u64 v[246:247], s[10:11], 0, v[0:1]
	global_load_dwordx4 v[152:155], v[246:247], off
	v_lshl_add_u64 v[246:247], s[10:11], 0, v[196:197]
	global_load_dwordx4 v[156:159], v[246:247], off
	s_add_i32 s34, s34, -1
; #define LAS __attribute__((address_space(3)))
; template <int DQK, int DV, int FLAGS, int qp, int kp, int vts, int op> ...
;     ...
;             __builtin_amdgcn_sched_barrier(0);
; #pragma unroll
;             for (int c = 0; c < ND0 / 2; ++c) {
;                 if (c + 1 < ND0 / 2) {
; #pragma unroll
;                     for (int i = 0; i < 2; ++i) { kf[(c + 1) & 1][2 * i] = *(const LAS bf16x8*)(kb + (2 * c + 2 + i) * 32); kf[(c + 1) & 1][2 * i + 1] = *(const LAS bf16x8*)(kb + 32 * KROW + (2 * c + 2 + i) * 32); }
;                 }
; #pragma unroll
;                 for (int i = 0; i < 2; ++i) {
;                     p0 = __builtin_amdgcn_mfma_f32_32x32x16_bf16(kf[c & 1][2 * i], qr[2 * c + i], p0, 0, 0, 0);
;                     p1 = __builtin_amdgcn_mfma_f32_32x32x16_bf16(kf[c & 1][2 * i + 1], qr[2 * c + i], p1, 0, 0, 0);
;                 }
;                 __builtin_amdgcn_sched_barrier(0);
;             }
;     ...
;             f32x2 rs2 = {0.f, 0.f};
; #pragma unroll
;             for (int r = 0; r < 16; ++r) { p0[r] = __builtin_amdgcn_exp2f(p0[r]); p1[r] = __builtin_amdgcn_exp2f(p1[r]); }
; #pragma unroll
;             for (int r = 0; r < 16; r += 2) { rs2 += (f32x2){p0[r], p0[r + 1]}; rs2 += (f32x2){p1[r], p1[r + 1]}; }
;             l += rs2.x + rs2.y;
;             bf16x8 pf[4];
;             pf[0] = pack_bf16x8(p0, 0); pf[1] = pack_bf16x8(p0, 8); pf[2] = pack_bf16x8(p1, 0); pf[3] = pack_bf16x8(p1, 8);
;             __builtin_amdgcn_sched_barrier(0);
; #pragma unroll
;             for (int d = 0; d < NDB; ++d) {
;                 if (d + 1 < NDB) {
; #pragma unroll
;                     for (int ks = 0; ks < 4; ++ks) vf[(d + 1) & 1][ks] = *(const LAS bf16x8*)(vb + (d + 1) * 32 * VROW + ks * 32);
;                 }
; #pragma unroll
;                 for (int ks = 0; ks < 4; ++ks) o[d] = __builtin_amdgcn_mfma_f32_32x32x16_bf16(vf[d & 1][ks], pf[ks], o[d], 0, 0, 0);
;                 __builtin_amdgcn_sched_barrier(0);
;             }
.Ld_nols_p0:
	s_cmp_le_i32 s23, s24
	s_cbranch_scc1 .Ld_gen0
	s_add_i32 s13, s23, 1
	s_cmp_ge_i32 s13, s3
	s_cbranch_scc1 .Ld_gen0
	s_add_i32 s12, s23, -1
	s_and_b32 s12, s12, 3
	s_mulk_i32 s12, 0x6c00
	v_add3_u32 v245, s12, v203, v194
	ds_read_b128 v[224:227], v245 offset:13824
	ds_read_b128 v[228:231], v245 offset:13856
	ds_read_b128 v[232:235], v245 offset:13888
	ds_read_b128 v[236:239], v245 offset:13920
	s_add_i32 s12, s23, 1
	s_and_b32 s12, s12, 3
	s_mulk_i32 s12, 0x6c00
	v_add3_u32 v244, s12, v201, v194
	s_and_b32 s12, s23, 3
	s_mulk_i32 s12, 0x6c00
	v_add3_u32 v251, s12, v203, v194
	v_mfma_f32_32x32x16_bf16 v[64:79], v[160:163], v[112:115], v[64:79]
	v_exp_f32_e32 v80, v80
	v_exp_f32_e32 v81, v81
	v_exp_f32_e32 v96, v96
	v_exp_f32_e32 v97, v97
	v_add_u32_e32 v246, 64, v205
	v_mov_b32_e32 v240, v80
	v_mfma_f32_32x32x16_bf16 v[64:79], v[164:167], v[116:119], v[64:79]
	v_mov_b32_e32 v241, v81
	v_exp_f32_e32 v82, v82
	v_exp_f32_e32 v83, v83
	v_cvt_f32_i32_e32 v246, v246
	v_add_f32_e32 v240, v96, v240
	v_add_f32_e32 v241, v97, v241
	v_mfma_f32_32x32x16_bf16 v[64:79], v[168:171], v[120:123], v[64:79]
	v_exp_f32_e32 v98, v98
	v_exp_f32_e32 v99, v99
	v_fma_f32 v242, -v14, v246, -v222
	v_add_f32_e32 v240, v82, v240
	v_add_f32_e32 v241, v83, v241
	v_exp_f32_e32 v84, v84
	v_mfma_f32_32x32x16_bf16 v[64:79], v[172:175], v[124:127], v[64:79]
	v_exp_f32_e32 v85, v85
	v_fma_f32 v128, v14, s8, v242
	v_add_f32_e32 v240, v98, v240
	v_add_f32_e32 v241, v99, v241
	v_exp_f32_e32 v100, v100
	v_exp_f32_e32 v101, v101
	ds_read_b128 v[160:163], v245 offset:18432
	ds_read_b128 v[164:167], v245 offset:18464
	ds_read_b128 v[168:171], v245 offset:18496
	ds_read_b128 v[172:175], v245 offset:18528
	s_waitcnt lgkmcnt(4)
	v_mfma_f32_32x32x16_bf16 v[48:63], v[224:227], v[112:115], v[48:63]
	v_fma_f32 v129, v14, s9, v242
	v_add_f32_e32 v240, v84, v240
	v_add_f32_e32 v241, v85, v241
	v_exp_f32_e32 v86, v86
	v_exp_f32_e32 v87, v87
	v_fma_f32 v130, v14, s96, v242
	v_mfma_f32_32x32x16_bf16 v[48:63], v[228:231], v[116:119], v[48:63]
	v_add_f32_e32 v240, v100, v240
	v_add_f32_e32 v241, v101, v241
	v_exp_f32_e32 v102, v102
	v_exp_f32_e32 v103, v103
	v_fma_f32 v131, v14, s97, v242
	v_add_f32_e32 v240, v86, v240
	v_mfma_f32_32x32x16_bf16 v[48:63], v[232:235], v[120:123], v[48:63]
	v_add_f32_e32 v241, v87, v241
	v_exp_f32_e32 v88, v88
	v_exp_f32_e32 v89, v89
	v_fma_f32 v132, v14, s94, v242
	v_add_f32_e32 v240, v102, v240
	v_add_f32_e32 v241, v103, v241
	v_mfma_f32_32x32x16_bf16 v[48:63], v[236:239], v[124:127], v[48:63]
	v_exp_f32_e32 v104, v104
	v_exp_f32_e32 v105, v105
	v_fma_f32 v133, v14, s95, v242
	v_add_f32_e32 v240, v88, v240
	v_add_f32_e32 v241, v89, v241
	v_exp_f32_e32 v90, v90
	ds_read_b128 v[224:227], v245 offset:23040
	ds_read_b128 v[228:231], v245 offset:23072
	ds_read_b128 v[232:235], v245 offset:23104
	ds_read_b128 v[236:239], v245 offset:23136
	s_waitcnt lgkmcnt(4)
	v_mfma_f32_32x32x16_bf16 v[32:47], v[160:163], v[112:115], v[32:47]
	v_exp_f32_e32 v91, v91
	v_fma_f32 v134, v14, s92, v242
	v_add_f32_e32 v240, v104, v240
	v_add_f32_e32 v241, v105, v241
	v_exp_f32_e32 v106, v106
	v_exp_f32_e32 v107, v107
	v_mfma_f32_32x32x16_bf16 v[32:47], v[164:167], v[116:119], v[32:47]
	v_fma_f32 v135, v14, s93, v242
	v_add_f32_e32 v240, v90, v240
	v_add_f32_e32 v241, v91, v241
	v_exp_f32_e32 v92, v92
	v_exp_f32_e32 v93, v93
	v_fma_f32 v136, v14, s90, v242
	v_mfma_f32_32x32x16_bf16 v[32:47], v[168:171], v[120:123], v[32:47]
	v_add_f32_e32 v240, v106, v240
	v_add_f32_e32 v241, v107, v241
	v_exp_f32_e32 v108, v108
	v_exp_f32_e32 v109, v109
	v_fma_f32 v137, v14, s91, v242
	v_add_f32_e32 v240, v92, v240
	v_mfma_f32_32x32x16_bf16 v[32:47], v[172:175], v[124:127], v[32:47]
	v_add_f32_e32 v241, v93, v241
	v_exp_f32_e32 v94, v94
	v_exp_f32_e32 v95, v95
	v_fma_f32 v138, v14, s88, v242
	v_add_f32_e32 v240, v108, v240
	v_add_f32_e32 v241, v109, v241
	ds_read_b128 v[160:163], v244 offset:4608
	ds_read_b128 v[164:167], v244 offset:4640
	ds_read_b128 v[168:171], v244 offset:4672
	ds_read_b128 v[172:175], v244 offset:4704
	s_waitcnt lgkmcnt(4)
	v_mfma_f32_32x32x16_bf16 v[16:31], v[224:227], v[112:115], v[16:31]
	v_exp_f32_e32 v110, v110
	v_exp_f32_e32 v111, v111
	v_fma_f32 v139, v14, s89, v242
	v_add_f32_e32 v240, v94, v240
	v_add_f32_e32 v241, v95, v241
	v_fma_f32 v140, v14, s86, v242
	v_mfma_f32_32x32x16_bf16 v[16:31], v[228:231], v[116:119], v[16:31]
	v_fma_f32 v141, v14, s87, v242
	v_fma_f32 v142, v14, s78, v242
	v_fma_f32 v143, v14, s79, v242
	v_mfma_f32_32x32x16_bf16 v[16:31], v[232:235], v[120:123], v[16:31]
	v_mfma_f32_32x32x16_bf16 v[16:31], v[236:239], v[124:127], v[16:31]
	ds_read_b128 v[224:227], v244 offset:0
	ds_read_b128 v[228:231], v244 offset:32
	ds_read_b128 v[232:235], v244 offset:64
	ds_read_b128 v[236:239], v244 offset:96
	s_waitcnt lgkmcnt(4)
	v_mfma_f32_32x32x16_bf16 v[128:143], v[160:163], v[2:5], v[128:143]
	v_mov_b32_e32 v112, v242
	v_add_f32_e32 v113, v14, v242
	v_fma_f32 v114, v14, s62, v242
	v_fma_f32 v115, v14, s63, v242
	v_mfma_f32_32x32x16_bf16 v[128:143], v[164:167], v[6:9], v[128:143]
	v_fma_f32 v116, v14, s64, v242
	v_fma_f32 v117, v14, s65, v242
	v_fma_f32 v118, v14, s66, v242
	v_fma_f32 v119, v14, s67, v242
	v_mfma_f32_32x32x16_bf16 v[128:143], v[168:171], v[10:13], v[128:143]
	v_fma_f32 v120, v14, s68, v242
	v_fma_f32 v121, v14, s69, v242
	v_fma_f32 v122, v14, s70, v242
	v_fma_f32 v123, v14, s71, v242
	v_mfma_f32_32x32x16_bf16 v[128:143], v[172:175], v[144:147], v[128:143]
	v_fma_f32 v124, v14, s72, v242
	v_fma_f32 v125, v14, s73, v242
	v_fma_f32 v126, v14, s76, v242
	v_fma_f32 v127, v14, s77, v242
	ds_read_b128 v[160:163], v251 offset:9216
	ds_read_b128 v[164:167], v251 offset:9248
	ds_read_b128 v[168:171], v251 offset:9280
	ds_read_b128 v[172:175], v251 offset:9312
	s_waitcnt lgkmcnt(4)
	v_mfma_f32_32x32x16_bf16 v[112:127], v[224:227], v[2:5], v[112:127]
	s_nop 0
	v_add_f32_e32 v240, v110, v240
	v_add_f32_e32 v241, v111, v241
	v_cvt_pk_bf16_f32 v80, v80, v81
	v_cvt_pk_bf16_f32 v81, v82, v83
	v_cvt_pk_bf16_f32 v82, v84, v85
	v_mfma_f32_32x32x16_bf16 v[112:127], v[228:231], v[6:9], v[112:127]
	v_cvt_pk_bf16_f32 v83, v86, v87
	v_cvt_pk_bf16_f32 v84, v88, v89
	v_cvt_pk_bf16_f32 v85, v90, v91
	v_cvt_pk_bf16_f32 v86, v92, v93
	v_cvt_pk_bf16_f32 v87, v94, v95
	v_cvt_pk_bf16_f32 v88, v96, v97
	v_mfma_f32_32x32x16_bf16 v[112:127], v[232:235], v[10:13], v[112:127]
	v_cvt_pk_bf16_f32 v89, v98, v99
	v_cvt_pk_bf16_f32 v90, v100, v101
	v_cvt_pk_bf16_f32 v91, v102, v103
	v_cvt_pk_bf16_f32 v92, v104, v105
	v_cvt_pk_bf16_f32 v93, v106, v107
	v_cvt_pk_bf16_f32 v94, v108, v109
	v_mfma_f32_32x32x16_bf16 v[112:127], v[236:239], v[144:147], v[112:127]
	v_cvt_pk_bf16_f32 v95, v110, v111
	v_add_f32_e32 v247, v240, v241
	v_add_f32_e32 v199, v199, v247
	s_branch .Ld_tail0

; #define ATT_LSTORE(buf) do { LAS unsigned char* b_ = lds + (buf) * BUF; \
;         _Pragma("unroll") for (int i = 0; i < KPT; ++i) { if (KCH % NTHREADS == 0 || tid + i * NTHREADS < KCH) *(LAS u32x4*)(b_ + klo[i]) = kreg[i]; } \
;         _Pragma("unroll") for (int i = 0; i < VPT; ++i) *(LAS u32x4*)(b_ + vlo[i]) = vreg[i]; } while (0)
; template <int DQK, int DV, int FLAGS, int qp, int kp, int vts, int op> ...
;     ...
;     for (int it = 0; it < ntile; ++it) {
;         const int t = (FLAGS & AF_REV) ? kt_hi - 1 - it : kt_lo + it;
;         const int cur = it & 1;
;         const bool more = (it + 1 < ntile);
;         const int kv0 = t * 64;
;     ...
;         if (more) ATT_LSTORE(cur ^ 1);
;         __syncthreads();
.Ld_nopre_p0:
.Ld_tail0:
	v_add_u32_e32 v205, 64, v205
	s_add_i32 s23, s23, 1
	s_cmp_ge_i32 s23, s3
	s_cbranch_scc1 .Ld_flush1
	s_waitcnt lgkmcnt(0)
	s_barrier

; #define LAS __attribute__((address_space(3)))
; template <int DQK, int DV, int FLAGS, int qp, int kp, int vts, int op> ...
;     ...
;             __builtin_amdgcn_sched_barrier(0);
; #pragma unroll
;             for (int c = 0; c < ND0 / 2; ++c) {
;                 if (c + 1 < ND0 / 2) {
; #pragma unroll
;                     for (int i = 0; i < 2; ++i) { kf[(c + 1) & 1][2 * i] = *(const LAS bf16x8*)(kb + (2 * c + 2 + i) * 32); kf[(c + 1) & 1][2 * i + 1] = *(const LAS bf16x8*)(kb + 32 * KROW + (2 * c + 2 + i) * 32); }
;                 }
; #pragma unroll
;                 for (int i = 0; i < 2; ++i) {
;                     p0 = __builtin_amdgcn_mfma_f32_32x32x16_bf16(kf[c & 1][2 * i], qr[2 * c + i], p0, 0, 0, 0);
;                     p1 = __builtin_amdgcn_mfma_f32_32x32x16_bf16(kf[c & 1][2 * i + 1], qr[2 * c + i], p1, 0, 0, 0);
;                 }
;                 __builtin_amdgcn_sched_barrier(0);
;             }
;     ...
;             f32x2 rs2 = {0.f, 0.f};
; #pragma unroll
;             for (int r = 0; r < 16; ++r) { p0[r] = __builtin_amdgcn_exp2f(p0[r]); p1[r] = __builtin_amdgcn_exp2f(p1[r]); }
; #pragma unroll
;             for (int r = 0; r < 16; r += 2) { rs2 += (f32x2){p0[r], p0[r + 1]}; rs2 += (f32x2){p1[r], p1[r + 1]}; }
;             l += rs2.x + rs2.y;
;             bf16x8 pf[4];
;             pf[0] = pack_bf16x8(p0, 0); pf[1] = pack_bf16x8(p0, 8); pf[2] = pack_bf16x8(p1, 0); pf[3] = pack_bf16x8(p1, 8);
;             __builtin_amdgcn_sched_barrier(0);
; #pragma unroll
;             for (int d = 0; d < NDB; ++d) {
;                 if (d + 1 < NDB) {
; #pragma unroll
;                     for (int ks = 0; ks < 4; ++ks) vf[(d + 1) & 1][ks] = *(const LAS bf16x8*)(vb + (d + 1) * 32 * VROW + ks * 32);
;                 }
; #pragma unroll
;                 for (int ks = 0; ks < 4; ++ks) o[d] = __builtin_amdgcn_mfma_f32_32x32x16_bf16(vf[d & 1][ks], pf[ks], o[d], 0, 0, 0);
;                 __builtin_amdgcn_sched_barrier(0);
;             }
.Ld_nols_p1:
	s_cmp_le_i32 s23, s24
	s_cbranch_scc1 .Ld_gen1
	s_add_i32 s13, s23, 1
	s_cmp_ge_i32 s13, s3
	s_cbranch_scc1 .Ld_gen1
	s_add_i32 s12, s23, -1
	s_and_b32 s12, s12, 3
	s_mulk_i32 s12, 0x6c00
	v_add3_u32 v245, s12, v203, v194
	ds_read_b128 v[224:227], v245 offset:13824
	ds_read_b128 v[228:231], v245 offset:13856
	ds_read_b128 v[232:235], v245 offset:13888
	ds_read_b128 v[236:239], v245 offset:13920
	s_add_i32 s12, s23, 1
	s_and_b32 s12, s12, 3
	s_mulk_i32 s12, 0x6c00
	v_add3_u32 v244, s12, v201, v194
	s_and_b32 s12, s23, 3
	s_mulk_i32 s12, 0x6c00
	v_add3_u32 v251, s12, v203, v194
	v_mfma_f32_32x32x16_bf16 v[64:79], v[160:163], v[80:83], v[64:79]
	v_exp_f32_e32 v112, v112
	v_exp_f32_e32 v113, v113
	v_exp_f32_e32 v128, v128
	v_exp_f32_e32 v129, v129
	v_add_u32_e32 v246, 64, v205
	v_mov_b32_e32 v240, v112
	v_mfma_f32_32x32x16_bf16 v[64:79], v[164:167], v[84:87], v[64:79]
	v_mov_b32_e32 v241, v113
	v_exp_f32_e32 v114, v114
	v_exp_f32_e32 v115, v115
	v_cvt_f32_i32_e32 v246, v246
	v_add_f32_e32 v240, v128, v240
	v_add_f32_e32 v241, v129, v241
	v_mfma_f32_32x32x16_bf16 v[64:79], v[168:171], v[88:91], v[64:79]
	v_exp_f32_e32 v130, v130
	v_exp_f32_e32 v131, v131
	v_fma_f32 v242, -v14, v246, -v222
	v_add_f32_e32 v240, v114, v240
	v_add_f32_e32 v241, v115, v241
	v_exp_f32_e32 v116, v116
	v_mfma_f32_32x32x16_bf16 v[64:79], v[172:175], v[92:95], v[64:79]
	v_exp_f32_e32 v117, v117
	v_fma_f32 v96, v14, s8, v242
	v_add_f32_e32 v240, v130, v240
	v_add_f32_e32 v241, v131, v241
	v_exp_f32_e32 v132, v132
	v_exp_f32_e32 v133, v133
	ds_read_b128 v[160:163], v245 offset:18432
	ds_read_b128 v[164:167], v245 offset:18464
	ds_read_b128 v[168:171], v245 offset:18496
	ds_read_b128 v[172:175], v245 offset:18528
	s_waitcnt lgkmcnt(4)
	v_mfma_f32_32x32x16_bf16 v[48:63], v[224:227], v[80:83], v[48:63]
	v_fma_f32 v97, v14, s9, v242
	v_add_f32_e32 v240, v116, v240
	v_add_f32_e32 v241, v117, v241
	v_exp_f32_e32 v118, v118
	v_exp_f32_e32 v119, v119
	v_fma_f32 v98, v14, s96, v242
	v_mfma_f32_32x32x16_bf16 v[48:63], v[228:231], v[84:87], v[48:63]
	v_add_f32_e32 v240, v132, v240
	v_add_f32_e32 v241, v133, v241
	v_exp_f32_e32 v134, v134
	v_exp_f32_e32 v135, v135
	v_fma_f32 v99, v14, s97, v242
	v_add_f32_e32 v240, v118, v240
	v_mfma_f32_32x32x16_bf16 v[48:63], v[232:235], v[88:91], v[48:63]
	v_add_f32_e32 v241, v119, v241
	v_exp_f32_e32 v120, v120
	v_exp_f32_e32 v121, v121
	v_fma_f32 v100, v14, s94, v242
	v_add_f32_e32 v240, v134, v240
	v_add_f32_e32 v241, v135, v241
	v_mfma_f32_32x32x16_bf16 v[48:63], v[236:239], v[92:95], v[48:63]
	v_exp_f32_e32 v136, v136
	v_exp_f32_e32 v137, v137
	v_fma_f32 v101, v14, s95, v242
	v_add_f32_e32 v240, v120, v240
	v_add_f32_e32 v241, v121, v241
	v_exp_f32_e32 v122, v122
	ds_read_b128 v[224:227], v245 offset:23040
	ds_read_b128 v[228:231], v245 offset:23072
	ds_read_b128 v[232:235], v245 offset:23104
	ds_read_b128 v[236:239], v245 offset:23136
	s_waitcnt lgkmcnt(4)
	v_mfma_f32_32x32x16_bf16 v[32:47], v[160:163], v[80:83], v[32:47]
	v_exp_f32_e32 v123, v123
	v_fma_f32 v102, v14, s92, v242
	v_add_f32_e32 v240, v136, v240
	v_add_f32_e32 v241, v137, v241
	v_exp_f32_e32 v138, v138
	v_exp_f32_e32 v139, v139
	v_mfma_f32_32x32x16_bf16 v[32:47], v[164:167], v[84:87], v[32:47]
	v_fma_f32 v103, v14, s93, v242
	v_add_f32_e32 v240, v122, v240
	v_add_f32_e32 v241, v123, v241
	v_exp_f32_e32 v124, v124
	v_exp_f32_e32 v125, v125
	v_fma_f32 v104, v14, s90, v242
	v_mfma_f32_32x32x16_bf16 v[32:47], v[168:171], v[88:91], v[32:47]
	v_add_f32_e32 v240, v138, v240
	v_add_f32_e32 v241, v139, v241
	v_exp_f32_e32 v140, v140
	v_exp_f32_e32 v141, v141
	v_fma_f32 v105, v14, s91, v242
	v_add_f32_e32 v240, v124, v240
	v_mfma_f32_32x32x16_bf16 v[32:47], v[172:175], v[92:95], v[32:47]
	v_add_f32_e32 v241, v125, v241
	v_exp_f32_e32 v126, v126
	v_exp_f32_e32 v127, v127
	v_fma_f32 v106, v14, s88, v242
	v_add_f32_e32 v240, v140, v240
	v_add_f32_e32 v241, v141, v241
	ds_read_b128 v[160:163], v244 offset:4608
	ds_read_b128 v[164:167], v244 offset:4640
	ds_read_b128 v[168:171], v244 offset:4672
	ds_read_b128 v[172:175], v244 offset:4704
	s_waitcnt lgkmcnt(4)
	v_mfma_f32_32x32x16_bf16 v[16:31], v[224:227], v[80:83], v[16:31]
	v_exp_f32_e32 v142, v142
	v_exp_f32_e32 v143, v143
	v_fma_f32 v107, v14, s89, v242
	v_add_f32_e32 v240, v126, v240
	v_add_f32_e32 v241, v127, v241
	v_fma_f32 v108, v14, s86, v242
	v_mfma_f32_32x32x16_bf16 v[16:31], v[228:231], v[84:87], v[16:31]
	v_fma_f32 v109, v14, s87, v242
	v_fma_f32 v110, v14, s78, v242
	v_fma_f32 v111, v14, s79, v242
	v_mfma_f32_32x32x16_bf16 v[16:31], v[232:235], v[88:91], v[16:31]
	v_mfma_f32_32x32x16_bf16 v[16:31], v[236:239], v[92:95], v[16:31]
	ds_read_b128 v[224:227], v244 offset:0
	ds_read_b128 v[228:231], v244 offset:32
	ds_read_b128 v[232:235], v244 offset:64
	ds_read_b128 v[236:239], v244 offset:96
	s_waitcnt lgkmcnt(4)
	v_mfma_f32_32x32x16_bf16 v[96:111], v[160:163], v[2:5], v[96:111]
	v_mov_b32_e32 v80, v242
	v_add_f32_e32 v81, v14, v242
	v_fma_f32 v82, v14, s62, v242
	v_fma_f32 v83, v14, s63, v242
	v_mfma_f32_32x32x16_bf16 v[96:111], v[164:167], v[6:9], v[96:111]
	v_fma_f32 v84, v14, s64, v242
	v_fma_f32 v85, v14, s65, v242
	v_fma_f32 v86, v14, s66, v242
	v_fma_f32 v87, v14, s67, v242
	v_mfma_f32_32x32x16_bf16 v[96:111], v[168:171], v[10:13], v[96:111]
	v_fma_f32 v88, v14, s68, v242
	v_fma_f32 v89, v14, s69, v242
	v_fma_f32 v90, v14, s70, v242
	v_fma_f32 v91, v14, s71, v242
	v_mfma_f32_32x32x16_bf16 v[96:111], v[172:175], v[144:147], v[96:111]
	v_fma_f32 v92, v14, s72, v242
	v_fma_f32 v93, v14, s73, v242
	v_fma_f32 v94, v14, s76, v242
	v_fma_f32 v95, v14, s77, v242
	ds_read_b128 v[160:163], v251 offset:9216
	ds_read_b128 v[164:167], v251 offset:9248
	ds_read_b128 v[168:171], v251 offset:9280
	ds_read_b128 v[172:175], v251 offset:9312
	s_waitcnt lgkmcnt(4)
	v_mfma_f32_32x32x16_bf16 v[80:95], v[224:227], v[2:5], v[80:95]
	s_nop 0
	v_add_f32_e32 v240, v142, v240
	v_add_f32_e32 v241, v143, v241
	v_cvt_pk_bf16_f32 v112, v112, v113
	v_cvt_pk_bf16_f32 v113, v114, v115
	v_cvt_pk_bf16_f32 v114, v116, v117
	v_mfma_f32_32x32x16_bf16 v[80:95], v[228:231], v[6:9], v[80:95]
	v_cvt_pk_bf16_f32 v115, v118, v119
	v_cvt_pk_bf16_f32 v116, v120, v121
	v_cvt_pk_bf16_f32 v117, v122, v123
	v_cvt_pk_bf16_f32 v118, v124, v125
	v_cvt_pk_bf16_f32 v119, v126, v127
	v_cvt_pk_bf16_f32 v120, v128, v129
	v_mfma_f32_32x32x16_bf16 v[80:95], v[232:235], v[10:13], v[80:95]
	v_cvt_pk_bf16_f32 v121, v130, v131
	v_cvt_pk_bf16_f32 v122, v132, v133
	v_cvt_pk_bf16_f32 v123, v134, v135
	v_cvt_pk_bf16_f32 v124, v136, v137
	v_cvt_pk_bf16_f32 v125, v138, v139
	v_cvt_pk_bf16_f32 v126, v140, v141
	v_mfma_f32_32x32x16_bf16 v[80:95], v[236:239], v[144:147], v[80:95]
	v_cvt_pk_bf16_f32 v127, v142, v143
	v_add_f32_e32 v247, v240, v241
	v_add_f32_e32 v199, v199, v247
	s_branch .Ld_tail1

; #define ATT_LSTORE(buf) do { LAS unsigned char* b_ = lds + (buf) * BUF; \
;         _Pragma("unroll") for (int i = 0; i < KPT; ++i) { if (KCH % NTHREADS == 0 || tid + i * NTHREADS < KCH) *(LAS u32x4*)(b_ + klo[i]) = kreg[i]; } \
;         _Pragma("unroll") for (int i = 0; i < VPT; ++i) *(LAS u32x4*)(b_ + vlo[i]) = vreg[i]; } while (0)
; template <int DQK, int DV, int FLAGS, int qp, int kp, int vts, int op> ...
;     ...
;     for (int it = 0; it < ntile; ++it) {
;         const int t = (FLAGS & AF_REV) ? kt_hi - 1 - it : kt_lo + it;
;         const int cur = it & 1;
;         const bool more = (it + 1 < ntile);
;         const int kv0 = t * 64;
;     ...
;         if (skip && more) ATT_GLOAD((FLAGS & AF_REV) ? t - 1 : t + 1);
;         if (more) ATT_LSTORE(cur ^ 1);
;         __syncthreads();
.Ld_nopre_p1:
.Ld_tail1:
	v_add_u32_e32 v205, 64, v205
	s_add_i32 s23, s23, 1
	s_cmp_ge_i32 s23, s3
	s_cbranch_scc1 .Ld_flush0
	s_waitcnt lgkmcnt(0)
	s_barrier
	s_branch .Ld_top0
